# hyena filter MLP hidden layers: weight loads of the two dot-product loops issued in batches of 33 / 32 with counted vmcnt (both layers), on top of the earlier de-serialised prologue
# speedup vs baseline: 1.0142x; 1.0035x over previous
; __device__ NOINL void prep_filters(const LAS Params* lp, int l, bool with_ctx, LAS unsigned char* lds) {
;     ...
;         { const int pp = tid >> 6, j = tid & 63; float s = b1[j];
; #pragma unroll 3
;           for (int e = 0; e < 33; ++e) s += zz[pp * 33 + e] * w1[e * 64 + j];
;           h1[pp * 64 + j] = sinf(f1[j] * s); }
.LBB0_114:
	global_load_dword v126, v[18:19], off offset:-256
	global_load_dword v127, v[18:19], off
	global_load_dword v128, v[18:19], off offset:256
	v_lshl_add_u64 v[18:19], v[18:19], 0, s[22:23]
	global_load_dword v129, v[18:19], off offset:-256
	global_load_dword v130, v[18:19], off
	global_load_dword v131, v[18:19], off offset:256
	v_lshl_add_u64 v[18:19], v[18:19], 0, s[22:23]
	global_load_dword v132, v[18:19], off offset:-256
	global_load_dword v133, v[18:19], off
	global_load_dword v134, v[18:19], off offset:256
	v_lshl_add_u64 v[18:19], v[18:19], 0, s[22:23]
	global_load_dword v135, v[18:19], off offset:-256
	global_load_dword v136, v[18:19], off
	global_load_dword v137, v[18:19], off offset:256
	v_lshl_add_u64 v[18:19], v[18:19], 0, s[22:23]
	global_load_dword v138, v[18:19], off offset:-256
	global_load_dword v139, v[18:19], off
	global_load_dword v140, v[18:19], off offset:256
	v_lshl_add_u64 v[18:19], v[18:19], 0, s[22:23]
	global_load_dword v141, v[18:19], off offset:-256
	global_load_dword v142, v[18:19], off
	global_load_dword v143, v[18:19], off offset:256
	v_lshl_add_u64 v[18:19], v[18:19], 0, s[22:23]
	global_load_dword v144, v[18:19], off offset:-256
	global_load_dword v145, v[18:19], off
	global_load_dword v146, v[18:19], off offset:256
	v_lshl_add_u64 v[18:19], v[18:19], 0, s[22:23]
	global_load_dword v147, v[18:19], off offset:-256
	global_load_dword v148, v[18:19], off
	global_load_dword v149, v[18:19], off offset:256
	v_lshl_add_u64 v[18:19], v[18:19], 0, s[22:23]
	global_load_dword v150, v[18:19], off offset:-256
	global_load_dword v151, v[18:19], off
	global_load_dword v152, v[18:19], off offset:256
	v_lshl_add_u64 v[18:19], v[18:19], 0, s[22:23]
	global_load_dword v153, v[18:19], off offset:-256
	global_load_dword v154, v[18:19], off
	global_load_dword v155, v[18:19], off offset:256
	v_lshl_add_u64 v[18:19], v[18:19], 0, s[22:23]
	global_load_dword v156, v[18:19], off offset:-256
	global_load_dword v157, v[18:19], off
	global_load_dword v158, v[18:19], off offset:256
	v_lshl_add_u64 v[18:19], v[18:19], 0, s[22:23]
	ds_read2_b32 v[120:121], v30 offset0:0 offset1:1
	ds_read_b32 v122, v30 offset:8
	ds_read2_b32 v[124:125], v30 offset0:3 offset1:4
	ds_read_b32 v123, v30 offset:20
	s_waitcnt lgkmcnt(2)
	s_waitcnt vmcnt(32)
	v_fmac_f32_e32 v2, v120, v126
	s_waitcnt vmcnt(31)
	v_fmac_f32_e32 v2, v121, v127
	s_waitcnt vmcnt(30)
	v_fmac_f32_e32 v2, v122, v128
	ds_read2_b32 v[120:121], v30 offset0:6 offset1:7
	ds_read_b32 v122, v30 offset:32
	s_waitcnt lgkmcnt(2)
	s_waitcnt vmcnt(29)
	v_fmac_f32_e32 v2, v124, v129
	s_waitcnt vmcnt(28)
	v_fmac_f32_e32 v2, v125, v130
	s_waitcnt vmcnt(27)
	v_fmac_f32_e32 v2, v123, v131
	ds_read2_b32 v[124:125], v30 offset0:9 offset1:10
	ds_read_b32 v123, v30 offset:44
	s_waitcnt lgkmcnt(2)
	s_waitcnt vmcnt(26)
	v_fmac_f32_e32 v2, v120, v132
	s_waitcnt vmcnt(25)
	v_fmac_f32_e32 v2, v121, v133
	s_waitcnt vmcnt(24)
	v_fmac_f32_e32 v2, v122, v134
	ds_read2_b32 v[120:121], v30 offset0:12 offset1:13
	ds_read_b32 v122, v30 offset:56
	s_waitcnt lgkmcnt(2)
	s_waitcnt vmcnt(23)
	v_fmac_f32_e32 v2, v124, v135
	s_waitcnt vmcnt(22)
	v_fmac_f32_e32 v2, v125, v136
	s_waitcnt vmcnt(21)
	v_fmac_f32_e32 v2, v123, v137
	ds_read2_b32 v[124:125], v30 offset0:15 offset1:16
	ds_read_b32 v123, v30 offset:68
	s_waitcnt lgkmcnt(2)
	s_waitcnt vmcnt(20)
	v_fmac_f32_e32 v2, v120, v138
	s_waitcnt vmcnt(19)
	v_fmac_f32_e32 v2, v121, v139
	s_waitcnt vmcnt(18)
	v_fmac_f32_e32 v2, v122, v140
	ds_read2_b32 v[120:121], v30 offset0:18 offset1:19
	ds_read_b32 v122, v30 offset:80
	s_waitcnt lgkmcnt(2)
	s_waitcnt vmcnt(17)
	v_fmac_f32_e32 v2, v124, v141
	s_waitcnt vmcnt(16)
	v_fmac_f32_e32 v2, v125, v142
	s_waitcnt vmcnt(15)
	v_fmac_f32_e32 v2, v123, v143
	ds_read2_b32 v[124:125], v30 offset0:21 offset1:22
	ds_read_b32 v123, v30 offset:92
	s_waitcnt lgkmcnt(2)
	s_waitcnt vmcnt(14)
	v_fmac_f32_e32 v2, v120, v144
	s_waitcnt vmcnt(13)
	v_fmac_f32_e32 v2, v121, v145
	s_waitcnt vmcnt(12)
	v_fmac_f32_e32 v2, v122, v146
	ds_read2_b32 v[120:121], v30 offset0:24 offset1:25
	ds_read_b32 v122, v30 offset:104
	s_waitcnt lgkmcnt(2)
	s_waitcnt vmcnt(11)
	v_fmac_f32_e32 v2, v124, v147
	s_waitcnt vmcnt(10)
	v_fmac_f32_e32 v2, v125, v148
	s_waitcnt vmcnt(9)
	v_fmac_f32_e32 v2, v123, v149
	ds_read2_b32 v[124:125], v30 offset0:27 offset1:28
	ds_read_b32 v123, v30 offset:116
	s_waitcnt lgkmcnt(2)
	s_waitcnt vmcnt(8)
	v_fmac_f32_e32 v2, v120, v150
	s_waitcnt vmcnt(7)
	v_fmac_f32_e32 v2, v121, v151
	s_waitcnt vmcnt(6)
	v_fmac_f32_e32 v2, v122, v152
	ds_read2_b32 v[120:121], v30 offset0:30 offset1:31
	ds_read_b32 v122, v30 offset:128
	s_waitcnt lgkmcnt(2)
	s_waitcnt vmcnt(5)
	v_fmac_f32_e32 v2, v124, v153
	s_waitcnt vmcnt(4)
	v_fmac_f32_e32 v2, v125, v154
	s_waitcnt vmcnt(3)
	v_fmac_f32_e32 v2, v123, v155
	s_waitcnt lgkmcnt(0)
	s_waitcnt vmcnt(2)
	v_fmac_f32_e32 v2, v120, v156
	s_waitcnt vmcnt(1)
	v_fmac_f32_e32 v2, v121, v157
	s_waitcnt vmcnt(0)
	v_fmac_f32_e32 v2, v122, v158
	s_movk_i32 s0, 0x84
	global_load_dword v18, v[6:7], off
	s_waitcnt vmcnt(0)
	v_mul_f32_e32 v18, v2, v18
	v_and_b32_e32 v19, 0x7fffffff, v18
	v_cmp_nlt_f32_e64 s[16:17], |v18|, s46
	s_and_saveexec_b64 s[18:19], s[16:17]
	s_xor_b64 s[30:31], exec, s[18:19]
	s_cbranch_execz .LBB0_117
; __device__ NOINL void prep_filters(const LAS Params* lp, int l, bool with_ctx, LAS unsigned char* lds) {
;     ...
;           h1[pp * 64 + j] = sinf(f1[j] * s); }
	v_lshrrev_b32_e32 v2, 23, v19
	v_add_u32_e32 v2, 0xffffff88, v2
	v_cmp_lt_u32_e32 vcc, 63, v2
	s_nop 1
	v_cndmask_b32_e32 v20, 0, v35, vcc
	v_add_u32_e32 v2, v20, v2
	v_cmp_lt_u32_e64 s[16:17], 31, v2
	s_nop 1
	v_cndmask_b32_e64 v20, 0, v36, s[16:17]
	v_add_u32_e32 v2, v20, v2
	v_cmp_lt_u32_e64 s[18:19], 31, v2
	s_nop 1
	v_cndmask_b32_e64 v20, 0, v36, s[18:19]
	v_add_u32_e32 v39, v20, v2
	v_and_b32_e32 v2, 0x7fffff, v19
	v_or_b32_e32 v44, 0x800000, v2
	v_mad_u64_u32 v[20:21], s[20:21], v44, s47, 0
	v_mov_b32_e32 v2, v21
	v_mad_u64_u32 v[22:23], s[20:21], v44, s48, v[2:3]
	v_mov_b32_e32 v2, v23
	v_mad_u64_u32 v[24:25], s[20:21], v44, s49, v[2:3]
	v_mov_b32_e32 v2, v25
	v_mad_u64_u32 v[26:27], s[20:21], v44, s50, v[2:3]
	v_mov_b32_e32 v2, v27
	v_mad_u64_u32 v[40:41], s[20:21], v44, s51, v[2:3]
	v_mov_b32_e32 v2, v41
	v_mad_u64_u32 v[42:43], s[20:21], v44, s53, v[2:3]
	v_mov_b32_e32 v2, v43
	v_mad_u64_u32 v[44:45], s[20:21], v44, s54, v[2:3]
	v_cndmask_b32_e32 v21, v42, v26, vcc
	v_cndmask_b32_e32 v2, v44, v40, vcc
	v_cndmask_b32_e32 v25, v45, v42, vcc
	v_cndmask_b32_e64 v23, v2, v21, s[16:17]
	v_cndmask_b32_e64 v2, v25, v2, s[16:17]
	v_cndmask_b32_e32 v25, v40, v24, vcc
	v_cndmask_b32_e64 v21, v21, v25, s[16:17]
	v_cndmask_b32_e32 v22, v26, v22, vcc
	v_cndmask_b32_e64 v2, v2, v23, s[18:19]
	v_cndmask_b32_e64 v23, v23, v21, s[18:19]
	v_sub_u32_e32 v27, 32, v39
	v_cndmask_b32_e64 v25, v25, v22, s[16:17]
	v_alignbit_b32 v40, v2, v23, v27
	v_cmp_eq_u32_e64 s[20:21], 0, v39
	v_cndmask_b32_e64 v21, v21, v25, s[18:19]
	v_cndmask_b32_e32 v20, v24, v20, vcc
	v_cndmask_b32_e64 v2, v40, v2, s[20:21]
	v_alignbit_b32 v26, v23, v21, v27
	v_cndmask_b32_e64 v20, v22, v20, s[16:17]
	v_cndmask_b32_e64 v23, v26, v23, s[20:21]
	v_bfe_u32 v40, v2, 29, 1
	v_cndmask_b32_e64 v20, v25, v20, s[18:19]
	v_alignbit_b32 v26, v2, v23, 30
	v_sub_u32_e32 v41, 0, v40
	v_alignbit_b32 v22, v21, v20, v27
	v_xor_b32_e32 v26, v26, v41
	v_cndmask_b32_e64 v21, v22, v21, s[20:21]
	v_alignbit_b32 v22, v23, v21, 30
	v_ffbh_u32_e32 v23, v26
	v_min_u32_e32 v23, 32, v23
	v_alignbit_b32 v20, v21, v20, 30
	v_xor_b32_e32 v22, v22, v41
	v_sub_u32_e32 v24, 31, v23
	v_xor_b32_e32 v20, v20, v41
	v_alignbit_b32 v25, v26, v22, v24
	v_alignbit_b32 v20, v22, v20, v24
	v_alignbit_b32 v21, v25, v20, 9
	v_ffbh_u32_e32 v22, v21
	v_min_u32_e32 v22, 32, v22
	v_lshrrev_b32_e32 v39, 29, v2
	v_not_b32_e32 v24, v22
	v_alignbit_b32 v20, v21, v20, v24
	v_lshlrev_b32_e32 v21, 31, v39
	v_or_b32_e32 v24, 0x33000000, v21
	v_add_lshl_u32 v22, v22, v23, 23
	v_lshrrev_b32_e32 v20, 9, v20
	v_sub_u32_e32 v22, v24, v22
	v_or_b32_e32 v21, 0.5, v21
	v_lshlrev_b32_e32 v23, 23, v23
	v_or_b32_e32 v20, v22, v20
	v_lshrrev_b32_e32 v22, 9, v25
	v_sub_u32_e32 v21, v21, v23
	v_or_b32_e32 v21, v22, v21
	v_mul_f32_e32 v22, 0x3fc90fda, v21
	v_fma_f32 v23, v21, s55, -v22
	v_fmac_f32_e32 v23, 0x33a22168, v21
	v_fmac_f32_e32 v23, 0x3fc90fda, v20
	v_lshrrev_b32_e32 v2, 30, v2
	v_add_f32_e32 v20, v22, v23
	v_add_u32_e32 v2, v40, v2

; __device__ NOINL void prep_filters(const LAS Params* lp, int l, bool with_ctx, LAS unsigned char* lds) {
;     ...
;         { const int pp = tid >> 6, j = tid & 63; float s = b2[j];
; #pragma unroll 4
;           for (int e = 0; e < 64; ++e) s += h1[pp * 64 + e] * w2[e * 64 + j];
;           h2[pp * 64 + j] = sinf(f2[j] * s); }
.LBB0_120:
	global_load_dword v130, v[18:19], off offset:-512
	global_load_dword v131, v[18:19], off offset:-256
	global_load_dword v132, v[18:19], off
	global_load_dword v133, v[18:19], off offset:256
	v_lshl_add_u64 v[18:19], v[18:19], 0, s[24:25]
	global_load_dword v134, v[18:19], off offset:-512
	global_load_dword v135, v[18:19], off offset:-256
	global_load_dword v136, v[18:19], off
	global_load_dword v137, v[18:19], off offset:256
	v_lshl_add_u64 v[18:19], v[18:19], 0, s[24:25]
	global_load_dword v138, v[18:19], off offset:-512
	global_load_dword v139, v[18:19], off offset:-256
	global_load_dword v140, v[18:19], off
	global_load_dword v141, v[18:19], off offset:256
	v_lshl_add_u64 v[18:19], v[18:19], 0, s[24:25]
	global_load_dword v142, v[18:19], off offset:-512
	global_load_dword v143, v[18:19], off offset:-256
	global_load_dword v144, v[18:19], off
	global_load_dword v145, v[18:19], off offset:256
	v_lshl_add_u64 v[18:19], v[18:19], 0, s[24:25]
	global_load_dword v146, v[18:19], off offset:-512
	global_load_dword v147, v[18:19], off offset:-256
	global_load_dword v148, v[18:19], off
	global_load_dword v149, v[18:19], off offset:256
	v_lshl_add_u64 v[18:19], v[18:19], 0, s[24:25]
	global_load_dword v150, v[18:19], off offset:-512
	global_load_dword v151, v[18:19], off offset:-256
	global_load_dword v152, v[18:19], off
	global_load_dword v153, v[18:19], off offset:256
	v_lshl_add_u64 v[18:19], v[18:19], 0, s[24:25]
	global_load_dword v154, v[18:19], off offset:-512
	global_load_dword v155, v[18:19], off offset:-256
	global_load_dword v156, v[18:19], off
	global_load_dword v157, v[18:19], off offset:256
	v_lshl_add_u64 v[18:19], v[18:19], 0, s[24:25]
	global_load_dword v158, v[18:19], off offset:-512
	global_load_dword v159, v[18:19], off offset:-256
	global_load_dword v160, v[18:19], off
	global_load_dword v161, v[18:19], off offset:256
	v_lshl_add_u64 v[18:19], v[18:19], 0, s[24:25]
	ds_read_b128 v[120:123], v32
	ds_read_b128 v[124:127], v32 offset:16
	s_waitcnt lgkmcnt(1)
	s_waitcnt vmcnt(31)
	v_fmac_f32_e32 v2, v120, v130
	s_waitcnt vmcnt(30)
	v_fmac_f32_e32 v2, v121, v131
	s_waitcnt vmcnt(29)
	v_fmac_f32_e32 v2, v122, v132
	s_waitcnt vmcnt(28)
	v_fmac_f32_e32 v2, v123, v133
	ds_read_b128 v[120:123], v32 offset:32
	s_waitcnt lgkmcnt(1)
	s_waitcnt vmcnt(27)
	v_fmac_f32_e32 v2, v124, v134
	s_waitcnt vmcnt(26)
	v_fmac_f32_e32 v2, v125, v135
	s_waitcnt vmcnt(25)
	v_fmac_f32_e32 v2, v126, v136
	s_waitcnt vmcnt(24)
	v_fmac_f32_e32 v2, v127, v137
	ds_read_b128 v[124:127], v32 offset:48
	s_waitcnt lgkmcnt(1)
	s_waitcnt vmcnt(23)
	v_fmac_f32_e32 v2, v120, v138
	s_waitcnt vmcnt(22)
	v_fmac_f32_e32 v2, v121, v139
	s_waitcnt vmcnt(21)
	v_fmac_f32_e32 v2, v122, v140
	s_waitcnt vmcnt(20)
	v_fmac_f32_e32 v2, v123, v141
	ds_read_b128 v[120:123], v32 offset:64
	s_waitcnt lgkmcnt(1)
	s_waitcnt vmcnt(19)
	v_fmac_f32_e32 v2, v124, v142
	s_waitcnt vmcnt(18)
	v_fmac_f32_e32 v2, v125, v143
	s_waitcnt vmcnt(17)
	v_fmac_f32_e32 v2, v126, v144
	s_waitcnt vmcnt(16)
	v_fmac_f32_e32 v2, v127, v145
	ds_read_b128 v[124:127], v32 offset:80
	s_waitcnt lgkmcnt(1)
	s_waitcnt vmcnt(15)
	v_fmac_f32_e32 v2, v120, v146
	s_waitcnt vmcnt(14)
	v_fmac_f32_e32 v2, v121, v147
	s_waitcnt vmcnt(13)
	v_fmac_f32_e32 v2, v122, v148
	s_waitcnt vmcnt(12)
	v_fmac_f32_e32 v2, v123, v149
	ds_read_b128 v[120:123], v32 offset:96
	s_waitcnt lgkmcnt(1)
	s_waitcnt vmcnt(11)
	v_fmac_f32_e32 v2, v124, v150
	s_waitcnt vmcnt(10)
	v_fmac_f32_e32 v2, v125, v151
	s_waitcnt vmcnt(9)
	v_fmac_f32_e32 v2, v126, v152
	s_waitcnt vmcnt(8)
	v_fmac_f32_e32 v2, v127, v153
	ds_read_b128 v[124:127], v32 offset:112
	s_waitcnt lgkmcnt(1)
	s_waitcnt vmcnt(7)
	v_fmac_f32_e32 v2, v120, v154
	s_waitcnt vmcnt(6)
	v_fmac_f32_e32 v2, v121, v155
	s_waitcnt vmcnt(5)
	v_fmac_f32_e32 v2, v122, v156
	s_waitcnt vmcnt(4)
	v_fmac_f32_e32 v2, v123, v157
	s_waitcnt lgkmcnt(0)
	s_waitcnt vmcnt(3)
	v_fmac_f32_e32 v2, v124, v158
	s_waitcnt vmcnt(2)
	v_fmac_f32_e32 v2, v125, v159
	s_waitcnt vmcnt(1)
	v_fmac_f32_e32 v2, v126, v160
	s_waitcnt vmcnt(0)
	v_fmac_f32_e32 v2, v127, v161
	global_load_dword v130, v[18:19], off offset:-512
	global_load_dword v131, v[18:19], off offset:-256
	global_load_dword v132, v[18:19], off
	global_load_dword v133, v[18:19], off offset:256
	v_lshl_add_u64 v[18:19], v[18:19], 0, s[24:25]
	global_load_dword v134, v[18:19], off offset:-512
	global_load_dword v135, v[18:19], off offset:-256
	global_load_dword v136, v[18:19], off
	global_load_dword v137, v[18:19], off offset:256
	v_lshl_add_u64 v[18:19], v[18:19], 0, s[24:25]
	global_load_dword v138, v[18:19], off offset:-512
	global_load_dword v139, v[18:19], off offset:-256
	global_load_dword v140, v[18:19], off
	global_load_dword v141, v[18:19], off offset:256
	v_lshl_add_u64 v[18:19], v[18:19], 0, s[24:25]
	global_load_dword v142, v[18:19], off offset:-512
	global_load_dword v143, v[18:19], off offset:-256
	global_load_dword v144, v[18:19], off
	global_load_dword v145, v[18:19], off offset:256
	v_lshl_add_u64 v[18:19], v[18:19], 0, s[24:25]
	global_load_dword v146, v[18:19], off offset:-512
	global_load_dword v147, v[18:19], off offset:-256
	global_load_dword v148, v[18:19], off
	global_load_dword v149, v[18:19], off offset:256
	v_lshl_add_u64 v[18:19], v[18:19], 0, s[24:25]
	global_load_dword v150, v[18:19], off offset:-512
	global_load_dword v151, v[18:19], off offset:-256
	global_load_dword v152, v[18:19], off
	global_load_dword v153, v[18:19], off offset:256
	v_lshl_add_u64 v[18:19], v[18:19], 0, s[24:25]
	global_load_dword v154, v[18:19], off offset:-512
	global_load_dword v155, v[18:19], off offset:-256
	global_load_dword v156, v[18:19], off
	global_load_dword v157, v[18:19], off offset:256
	v_lshl_add_u64 v[18:19], v[18:19], 0, s[24:25]
	global_load_dword v158, v[18:19], off offset:-512
	global_load_dword v159, v[18:19], off offset:-256
	global_load_dword v160, v[18:19], off
	global_load_dword v161, v[18:19], off offset:256
	v_lshl_add_u64 v[18:19], v[18:19], 0, s[24:25]
	ds_read_b128 v[120:123], v32 offset:128
	ds_read_b128 v[124:127], v32 offset:144
	s_waitcnt lgkmcnt(1)
; __device__ NOINL void prep_filters(const LAS Params* lp, int l, bool with_ctx, LAS unsigned char* lds) {
;     ...
;         { const int pp = tid >> 6, j = tid & 63; float s = b2[j];
; #pragma unroll 4
;           for (int e = 0; e < 64; ++e) s += h1[pp * 64 + e] * w2[e * 64 + j];
;           h2[pp * 64 + j] = sinf(f2[j] * s); }
	s_waitcnt vmcnt(31)
	v_fmac_f32_e32 v2, v120, v130
	s_waitcnt vmcnt(30)
	v_fmac_f32_e32 v2, v121, v131
	s_waitcnt vmcnt(29)
	v_fmac_f32_e32 v2, v122, v132
	s_waitcnt vmcnt(28)
	v_fmac_f32_e32 v2, v123, v133
	ds_read_b128 v[120:123], v32 offset:160
	s_waitcnt lgkmcnt(1)
	s_waitcnt vmcnt(27)
	v_fmac_f32_e32 v2, v124, v134
	s_waitcnt vmcnt(26)
	v_fmac_f32_e32 v2, v125, v135
	s_waitcnt vmcnt(25)
	v_fmac_f32_e32 v2, v126, v136
	s_waitcnt vmcnt(24)
	v_fmac_f32_e32 v2, v127, v137
	ds_read_b128 v[124:127], v32 offset:176
	s_waitcnt lgkmcnt(1)
	s_waitcnt vmcnt(23)
	v_fmac_f32_e32 v2, v120, v138
	s_waitcnt vmcnt(22)
	v_fmac_f32_e32 v2, v121, v139
	s_waitcnt vmcnt(21)
	v_fmac_f32_e32 v2, v122, v140
	s_waitcnt vmcnt(20)
	v_fmac_f32_e32 v2, v123, v141
	ds_read_b128 v[120:123], v32 offset:192
	s_waitcnt lgkmcnt(1)
	s_waitcnt vmcnt(19)
	v_fmac_f32_e32 v2, v124, v142
	s_waitcnt vmcnt(18)
	v_fmac_f32_e32 v2, v125, v143
	s_waitcnt vmcnt(17)
	v_fmac_f32_e32 v2, v126, v144
	s_waitcnt vmcnt(16)
	v_fmac_f32_e32 v2, v127, v145
	ds_read_b128 v[124:127], v32 offset:208
	s_waitcnt lgkmcnt(1)
	s_waitcnt vmcnt(15)
	v_fmac_f32_e32 v2, v120, v146
	s_waitcnt vmcnt(14)
	v_fmac_f32_e32 v2, v121, v147
	s_waitcnt vmcnt(13)
	v_fmac_f32_e32 v2, v122, v148
	s_waitcnt vmcnt(12)
	v_fmac_f32_e32 v2, v123, v149
	ds_read_b128 v[120:123], v32 offset:224
	s_waitcnt lgkmcnt(1)
	s_waitcnt vmcnt(11)
	v_fmac_f32_e32 v2, v124, v150
	s_waitcnt vmcnt(10)
	v_fmac_f32_e32 v2, v125, v151
	s_waitcnt vmcnt(9)
	v_fmac_f32_e32 v2, v126, v152
	s_waitcnt vmcnt(8)
	v_fmac_f32_e32 v2, v127, v153
	ds_read_b128 v[124:127], v32 offset:240
	s_waitcnt lgkmcnt(1)
	s_waitcnt vmcnt(7)
	v_fmac_f32_e32 v2, v120, v154
	s_waitcnt vmcnt(6)
	v_fmac_f32_e32 v2, v121, v155
	s_waitcnt vmcnt(5)
	v_fmac_f32_e32 v2, v122, v156
	s_waitcnt vmcnt(4)
	v_fmac_f32_e32 v2, v123, v157
	s_waitcnt lgkmcnt(0)
	s_waitcnt vmcnt(3)
	v_fmac_f32_e32 v2, v124, v158
	s_waitcnt vmcnt(2)
	v_fmac_f32_e32 v2, v125, v159
	s_waitcnt vmcnt(1)
	v_fmac_f32_e32 v2, v126, v160
	s_waitcnt vmcnt(0)
	v_fmac_f32_e32 v2, v127, v161
	s_movk_i32 s0, 0x100
	global_load_dword v18, v[10:11], off
	s_waitcnt vmcnt(0)
	v_mul_f32_e32 v18, v2, v18
	v_and_b32_e32 v19, 0x7fffffff, v18
	v_cmp_nlt_f32_e64 s[16:17], |v18|, s46
	s_and_saveexec_b64 s[18:19], s[16:17]
	s_xor_b64 s[30:31], exec, s[18:19]
	s_cbranch_execz .LBB0_123
	v_lshrrev_b32_e32 v2, 23, v19
	v_add_u32_e32 v2, 0xffffff88, v2
	v_cmp_lt_u32_e32 vcc, 63, v2
	s_nop 1
	v_cndmask_b32_e32 v20, 0, v35, vcc
	v_add_u32_e32 v2, v20, v2
	v_cmp_lt_u32_e64 s[16:17], 31, v2
	s_nop 1
	v_cndmask_b32_e64 v20, 0, v36, s[16:17]
	v_add_u32_e32 v2, v20, v2
	v_cmp_lt_u32_e64 s[18:19], 31, v2
	s_nop 1
	v_cndmask_b32_e64 v20, 0, v36, s[18:19]
	v_add_u32_e32 v39, v20, v2
	v_and_b32_e32 v2, 0x7fffff, v19
	v_or_b32_e32 v44, 0x800000, v2
	v_mad_u64_u32 v[20:21], s[20:21], v44, s47, 0
	v_mov_b32_e32 v2, v21
	v_mad_u64_u32 v[22:23], s[20:21], v44, s48, v[2:3]
	v_mov_b32_e32 v2, v23
	v_mad_u64_u32 v[24:25], s[20:21], v44, s49, v[2:3]
	v_mov_b32_e32 v2, v25
	v_mad_u64_u32 v[26:27], s[20:21], v44, s50, v[2:3]
	v_mov_b32_e32 v2, v27
	v_mad_u64_u32 v[40:41], s[20:21], v44, s51, v[2:3]
	v_mov_b32_e32 v2, v41
	v_mad_u64_u32 v[42:43], s[20:21], v44, s53, v[2:3]
	v_mov_b32_e32 v2, v43
	v_mad_u64_u32 v[44:45], s[20:21], v44, s54, v[2:3]
	v_cndmask_b32_e32 v21, v42, v26, vcc
	v_cndmask_b32_e32 v2, v44, v40, vcc
	v_cndmask_b32_e32 v25, v45, v42, vcc
	v_cndmask_b32_e64 v23, v2, v21, s[16:17]
	v_cndmask_b32_e64 v2, v25, v2, s[16:17]
	v_cndmask_b32_e32 v25, v40, v24, vcc
	v_cndmask_b32_e64 v21, v21, v25, s[16:17]
	v_cndmask_b32_e32 v22, v26, v22, vcc
	v_cndmask_b32_e64 v2, v2, v23, s[18:19]
	v_cndmask_b32_e64 v23, v23, v21, s[18:19]
	v_sub_u32_e32 v27, 32, v39
	v_cndmask_b32_e64 v25, v25, v22, s[16:17]
	v_alignbit_b32 v40, v2, v23, v27
	v_cmp_eq_u32_e64 s[20:21], 0, v39
	v_cndmask_b32_e64 v21, v21, v25, s[18:19]
	v_cndmask_b32_e32 v20, v24, v20, vcc
	v_cndmask_b32_e64 v2, v40, v2, s[20:21]
	v_alignbit_b32 v26, v23, v21, v27
	v_cndmask_b32_e64 v20, v22, v20, s[16:17]
	v_cndmask_b32_e64 v23, v26, v23, s[20:21]
	v_bfe_u32 v40, v2, 29, 1
	v_cndmask_b32_e64 v20, v25, v20, s[18:19]
	v_alignbit_b32 v26, v2, v23, 30
	v_sub_u32_e32 v41, 0, v40
	v_alignbit_b32 v22, v21, v20, v27
	v_xor_b32_e32 v26, v26, v41
	v_cndmask_b32_e64 v21, v22, v21, s[20:21]
	v_alignbit_b32 v22, v23, v21, 30
	v_ffbh_u32_e32 v23, v26
	v_min_u32_e32 v23, 32, v23
	v_alignbit_b32 v20, v21, v20, 30
	v_xor_b32_e32 v22, v22, v41
	v_sub_u32_e32 v24, 31, v23
	v_xor_b32_e32 v20, v20, v41
	v_alignbit_b32 v25, v26, v22, v24
	v_alignbit_b32 v20, v22, v20, v24
	v_alignbit_b32 v21, v25, v20, 9
	v_ffbh_u32_e32 v22, v21
	v_min_u32_e32 v22, 32, v22
	v_lshrrev_b32_e32 v39, 29, v2
	v_not_b32_e32 v24, v22
	v_alignbit_b32 v20, v21, v20, v24
	v_lshlrev_b32_e32 v21, 31, v39
	v_or_b32_e32 v24, 0x33000000, v21
	v_add_lshl_u32 v22, v22, v23, 23
	v_lshrrev_b32_e32 v20, 9, v20
	v_sub_u32_e32 v22, v24, v22
	v_or_b32_e32 v21, 0.5, v21
	v_lshlrev_b32_e32 v23, 23, v23
	v_or_b32_e32 v20, v22, v20
	v_lshrrev_b32_e32 v22, 9, v25
	v_sub_u32_e32 v21, v21, v23
	v_or_b32_e32 v21, v22, v21
	v_mul_f32_e32 v22, 0x3fc90fda, v21
	v_fma_f32 v23, v21, s55, -v22
	v_fmac_f32_e32 v23, 0x33a22168, v21
	v_fmac_f32_e32 v23, 0x3fc90fda, v20
	v_lshrrev_b32_e32 v2, 30, v2
	v_add_f32_e32 v20, v22, v23
	v_add_u32_e32 v2, v40, v2

; __device__ NOINL void prep_filters(const LAS Params* lp, int l, bool with_ctx, LAS unsigned char* lds) {
;     ...
;         { const int pp = tid >> 6, j = tid & 63; float s = b1[j];
; #pragma unroll 3
;           for (int e = 0; e < 33; ++e) s += zz[pp * 33 + e] * w1[e * 64 + j];
;           h1[pp * 64 + j] = sinf(f1[j] * s); }
.LBB0_419:
	s_mov_b64 s[4:5], 0x300
	global_load_dword v171, v[20:21], off offset:-512
	global_load_dword v172, v[20:21], off offset:-256
	global_load_dword v173, v[20:21], off
	v_lshl_add_u64 v[20:21], v[20:21], 0, s[4:5]
	global_load_dword v174, v[20:21], off offset:-512
	global_load_dword v175, v[20:21], off offset:-256
	global_load_dword v176, v[20:21], off
	v_lshl_add_u64 v[20:21], v[20:21], 0, s[4:5]
	global_load_dword v177, v[20:21], off offset:-512
	global_load_dword v178, v[20:21], off offset:-256
	global_load_dword v179, v[20:21], off
	v_lshl_add_u64 v[20:21], v[20:21], 0, s[4:5]
	global_load_dword v180, v[20:21], off offset:-512
	global_load_dword v181, v[20:21], off offset:-256
	global_load_dword v182, v[20:21], off
	v_lshl_add_u64 v[20:21], v[20:21], 0, s[4:5]
	global_load_dword v183, v[20:21], off offset:-512
	global_load_dword v185, v[20:21], off offset:-256
	global_load_dword v186, v[20:21], off
	v_lshl_add_u64 v[20:21], v[20:21], 0, s[4:5]
	global_load_dword v187, v[20:21], off offset:-512
	global_load_dword v188, v[20:21], off offset:-256
	global_load_dword v189, v[20:21], off
	v_lshl_add_u64 v[20:21], v[20:21], 0, s[4:5]
	global_load_dword v190, v[20:21], off offset:-512
	global_load_dword v191, v[20:21], off offset:-256
	global_load_dword v192, v[20:21], off
	v_lshl_add_u64 v[20:21], v[20:21], 0, s[4:5]
	global_load_dword v193, v[20:21], off offset:-512
	global_load_dword v194, v[20:21], off offset:-256
	global_load_dword v195, v[20:21], off
	v_lshl_add_u64 v[20:21], v[20:21], 0, s[4:5]
	global_load_dword v196, v[20:21], off offset:-512
	global_load_dword v197, v[20:21], off offset:-256
	global_load_dword v198, v[20:21], off
	v_lshl_add_u64 v[20:21], v[20:21], 0, s[4:5]
	global_load_dword v199, v[20:21], off offset:-512
	global_load_dword v200, v[20:21], off offset:-256
	global_load_dword v201, v[20:21], off
	v_lshl_add_u64 v[20:21], v[20:21], 0, s[4:5]
	global_load_dword v234, v[20:21], off offset:-512
	global_load_dword v235, v[20:21], off offset:-256
	global_load_dword v236, v[20:21], off
	v_lshl_add_u64 v[20:21], v[20:21], 0, s[4:5]
	ds_read2_b32 v[166:167], v34 offset0:0 offset1:1
	ds_read_b32 v165, v34 offset:8
	ds_read2_b32 v[168:169], v34 offset0:3 offset1:4
	ds_read_b32 v170, v34 offset:20
	s_waitcnt lgkmcnt(2)
	s_waitcnt vmcnt(32)
	v_fmac_f32_e32 v0, v166, v171
	s_waitcnt vmcnt(31)
	v_fmac_f32_e32 v0, v167, v172
	s_waitcnt vmcnt(30)
	v_fmac_f32_e32 v0, v165, v173
	ds_read2_b32 v[166:167], v34 offset0:6 offset1:7
	ds_read_b32 v165, v34 offset:32
	s_waitcnt lgkmcnt(2)
	s_waitcnt vmcnt(29)
	v_fmac_f32_e32 v0, v168, v174
	s_waitcnt vmcnt(28)
	v_fmac_f32_e32 v0, v169, v175
	s_waitcnt vmcnt(27)
	v_fmac_f32_e32 v0, v170, v176
	ds_read2_b32 v[168:169], v34 offset0:9 offset1:10
	ds_read_b32 v170, v34 offset:44
	s_waitcnt lgkmcnt(2)
	s_waitcnt vmcnt(26)
	v_fmac_f32_e32 v0, v166, v177
	s_waitcnt vmcnt(25)
	v_fmac_f32_e32 v0, v167, v178
	s_waitcnt vmcnt(24)
	v_fmac_f32_e32 v0, v165, v179
	ds_read2_b32 v[166:167], v34 offset0:12 offset1:13
	ds_read_b32 v165, v34 offset:56
	s_waitcnt lgkmcnt(2)
	s_waitcnt vmcnt(23)
	v_fmac_f32_e32 v0, v168, v180
	s_waitcnt vmcnt(22)
	v_fmac_f32_e32 v0, v169, v181
	s_waitcnt vmcnt(21)
	v_fmac_f32_e32 v0, v170, v182
	ds_read2_b32 v[168:169], v34 offset0:15 offset1:16
	ds_read_b32 v170, v34 offset:68
	s_waitcnt lgkmcnt(2)
	s_waitcnt vmcnt(20)
	v_fmac_f32_e32 v0, v166, v183
	s_waitcnt vmcnt(19)
	v_fmac_f32_e32 v0, v167, v185
	s_waitcnt vmcnt(18)
	v_fmac_f32_e32 v0, v165, v186
	ds_read2_b32 v[166:167], v34 offset0:18 offset1:19
	ds_read_b32 v165, v34 offset:80
	s_waitcnt lgkmcnt(2)
	s_waitcnt vmcnt(17)
	v_fmac_f32_e32 v0, v168, v187
	s_waitcnt vmcnt(16)
	v_fmac_f32_e32 v0, v169, v188
	s_waitcnt vmcnt(15)
	v_fmac_f32_e32 v0, v170, v189
	ds_read2_b32 v[168:169], v34 offset0:21 offset1:22
	ds_read_b32 v170, v34 offset:92
	s_waitcnt lgkmcnt(2)
	s_waitcnt vmcnt(14)
	v_fmac_f32_e32 v0, v166, v190
	s_waitcnt vmcnt(13)
	v_fmac_f32_e32 v0, v167, v191
	s_waitcnt vmcnt(12)
	v_fmac_f32_e32 v0, v165, v192
	ds_read2_b32 v[166:167], v34 offset0:24 offset1:25
	ds_read_b32 v165, v34 offset:104
	s_waitcnt lgkmcnt(2)
	s_waitcnt vmcnt(11)
	v_fmac_f32_e32 v0, v168, v193
	s_waitcnt vmcnt(10)
	v_fmac_f32_e32 v0, v169, v194
	s_waitcnt vmcnt(9)
	v_fmac_f32_e32 v0, v170, v195
	ds_read2_b32 v[168:169], v34 offset0:27 offset1:28
	ds_read_b32 v170, v34 offset:116
	s_waitcnt lgkmcnt(2)
	s_waitcnt vmcnt(8)
	v_fmac_f32_e32 v0, v166, v196
	s_waitcnt vmcnt(7)
	v_fmac_f32_e32 v0, v167, v197
	s_waitcnt vmcnt(6)
	v_fmac_f32_e32 v0, v165, v198
	ds_read2_b32 v[166:167], v34 offset0:30 offset1:31
	ds_read_b32 v165, v34 offset:128
	s_waitcnt lgkmcnt(2)
	s_waitcnt vmcnt(5)
	v_fmac_f32_e32 v0, v168, v199
	s_waitcnt vmcnt(4)
	v_fmac_f32_e32 v0, v169, v200
	s_waitcnt vmcnt(3)
	v_fmac_f32_e32 v0, v170, v201
	s_waitcnt lgkmcnt(0)
	s_waitcnt vmcnt(2)
	v_fmac_f32_e32 v0, v166, v234
	s_waitcnt vmcnt(1)
	v_fmac_f32_e32 v0, v167, v235
	s_waitcnt vmcnt(0)
	v_fmac_f32_e32 v0, v165, v236
	s_movk_i32 s1, 0x84
	global_load_dword v20, v[8:9], off offset:256
	s_brev_b32 s1, 18
	s_waitcnt vmcnt(0)
	v_mul_f32_e32 v20, v0, v20
	v_and_b32_e32 v21, 0x7fffffff, v20
	v_cmp_nlt_f32_e64 s[4:5], |v20|, s1
	s_and_saveexec_b64 s[18:19], s[4:5]
	s_xor_b64 s[58:59], exec, s[18:19]
	s_cbranch_execz .LBB0_422
; __device__ NOINL void prep_filters(const LAS Params* lp, int l, bool with_ctx, LAS unsigned char* lds) {
;     ...
;           h1[pp * 64 + j] = sinf(f1[j] * s); }
	v_lshrrev_b32_e32 v0, 23, v21
	v_add_u32_e32 v0, 0xffffff88, v0
	v_cmp_lt_u32_e32 vcc, 63, v0
	s_mov_b32 s1, 0xfe5163ab
	s_nop 0
	v_cndmask_b32_e32 v22, 0, v221, vcc
	v_add_u32_e32 v0, v22, v0
	v_cmp_lt_u32_e64 s[52:53], 31, v0
	s_nop 1
	v_cndmask_b32_e64 v22, 0, v222, s[52:53]
	v_add_u32_e32 v0, v22, v0
	v_cmp_lt_u32_e64 s[54:55], 31, v0
	s_nop 1
	v_cndmask_b32_e64 v22, 0, v222, s[54:55]
	v_add_u32_e32 v37, v22, v0
	v_and_b32_e32 v0, 0x7fffff, v21
	v_or_b32_e32 v42, 0x800000, v0
	v_mad_u64_u32 v[22:23], s[4:5], v42, s1, 0
	v_mov_b32_e32 v0, v23
	s_mov_b32 s1, 0x3c439041
	v_mad_u64_u32 v[24:25], s[4:5], v42, s1, v[0:1]
	v_mov_b32_e32 v0, v25
	s_mov_b32 s1, 0xdb629599
	v_mad_u64_u32 v[26:27], s[4:5], v42, s1, v[0:1]
	v_mov_b32_e32 v0, v27
	s_mov_b32 s1, 0xf534ddc0
	v_mad_u64_u32 v[28:29], s[4:5], v42, s1, v[0:1]
	v_mov_b32_e32 v0, v29
	s_mov_b32 s1, 0xfc2757d1
	v_mad_u64_u32 v[38:39], s[4:5], v42, s1, v[0:1]
	v_mov_b32_e32 v0, v39
	s_mov_b32 s1, 0x4e441529
	v_mad_u64_u32 v[40:41], s[4:5], v42, s1, v[0:1]
	v_mov_b32_e32 v0, v41
	s_mov_b32 s1, 0xa2f9836e
	v_mad_u64_u32 v[42:43], s[4:5], v42, s1, v[0:1]
	v_cndmask_b32_e32 v23, v40, v28, vcc
	v_cndmask_b32_e32 v0, v42, v38, vcc
	v_cndmask_b32_e32 v27, v43, v40, vcc
	v_cndmask_b32_e64 v25, v0, v23, s[52:53]
	v_cndmask_b32_e64 v0, v27, v0, s[52:53]
	v_cndmask_b32_e32 v27, v38, v26, vcc
	v_cndmask_b32_e64 v23, v23, v27, s[52:53]
	v_cndmask_b32_e32 v24, v28, v24, vcc
	v_cndmask_b32_e64 v0, v0, v25, s[54:55]
	v_cndmask_b32_e64 v25, v25, v23, s[54:55]
	v_sub_u32_e32 v29, 32, v37
	v_cndmask_b32_e64 v27, v27, v24, s[52:53]
	v_alignbit_b32 v38, v0, v25, v29
	v_cmp_eq_u32_e64 s[56:57], 0, v37
	v_cndmask_b32_e64 v23, v23, v27, s[54:55]
	v_cndmask_b32_e32 v22, v26, v22, vcc
	v_cndmask_b32_e64 v0, v38, v0, s[56:57]
	v_alignbit_b32 v28, v25, v23, v29
	v_cndmask_b32_e64 v22, v24, v22, s[52:53]
	v_cndmask_b32_e64 v25, v28, v25, s[56:57]
	v_bfe_u32 v38, v0, 29, 1
	v_cndmask_b32_e64 v22, v27, v22, s[54:55]
	v_alignbit_b32 v28, v0, v25, 30
	v_sub_u32_e32 v39, 0, v38
	v_alignbit_b32 v24, v23, v22, v29
	v_xor_b32_e32 v28, v28, v39
	v_cndmask_b32_e64 v23, v24, v23, s[56:57]
	v_alignbit_b32 v24, v25, v23, 30
	v_ffbh_u32_e32 v25, v28
	v_min_u32_e32 v25, 32, v25
	v_alignbit_b32 v22, v23, v22, 30
	v_xor_b32_e32 v24, v24, v39
	v_sub_u32_e32 v26, 31, v25
	v_xor_b32_e32 v22, v22, v39
	v_alignbit_b32 v27, v28, v24, v26
	v_alignbit_b32 v22, v24, v22, v26
	v_alignbit_b32 v23, v27, v22, 9
	v_ffbh_u32_e32 v24, v23
	v_min_u32_e32 v24, 32, v24
	v_lshrrev_b32_e32 v37, 29, v0
	v_not_b32_e32 v26, v24
	v_alignbit_b32 v22, v23, v22, v26
	v_lshlrev_b32_e32 v23, 31, v37
	v_or_b32_e32 v26, 0x33000000, v23
	v_add_lshl_u32 v24, v24, v25, 23
	v_lshrrev_b32_e32 v22, 9, v22
	v_sub_u32_e32 v24, v26, v24
	v_or_b32_e32 v23, 0.5, v23
	v_lshlrev_b32_e32 v25, 23, v25
	v_or_b32_e32 v22, v24, v22
	v_lshrrev_b32_e32 v24, 9, v27
	v_sub_u32_e32 v23, v23, v25
	v_or_b32_e32 v23, v24, v23
	v_mul_f32_e32 v24, 0x3fc90fda, v23
	s_mov_b32 s1, 0x3fc90fda
	v_fma_f32 v25, v23, s1, -v24
	v_fmac_f32_e32 v25, 0x33a22168, v23
	v_fmac_f32_e32 v25, 0x3fc90fda, v22
	v_lshrrev_b32_e32 v0, 30, v0
	v_add_f32_e32 v22, v24, v25
	v_add_u32_e32 v0, v38, v0

; __device__ NOINL void prep_filters(const LAS Params* lp, int l, bool with_ctx, LAS unsigned char* lds) {
;     ...
;         { const int pp = tid >> 6, j = tid & 63; float s = b2[j];
; #pragma unroll 4
;           for (int e = 0; e < 64; ++e) s += h1[pp * 64 + e] * w2[e * 64 + j];
;           h2[pp * 64 + j] = sinf(f2[j] * s); }
.LBB0_425:
	v_lshl_add_u64 v[174:175], v[18:19], 0, s[52:53]
	v_add_co_u32_e32 v174, vcc, 0x4000, v174
	s_nop 1
	v_addc_co_u32_e32 v175, vcc, 0, v175, vcc
	global_load_dword v165, v[174:175], off
	global_load_dword v176, v[174:175], off offset:256
	global_load_dword v177, v[174:175], off offset:512
	global_load_dword v178, v[174:175], off offset:768
	v_add_co_u32_e32 v174, vcc, 0x400, v174
	s_nop 1
	v_addc_co_u32_e32 v175, vcc, 0, v175, vcc
	global_load_dword v179, v[174:175], off
	global_load_dword v180, v[174:175], off offset:256
	global_load_dword v181, v[174:175], off offset:512
	global_load_dword v182, v[174:175], off offset:768
	v_add_co_u32_e32 v174, vcc, 0x400, v174
	s_nop 1
	v_addc_co_u32_e32 v175, vcc, 0, v175, vcc
	global_load_dword v183, v[174:175], off
	global_load_dword v185, v[174:175], off offset:256
	global_load_dword v186, v[174:175], off offset:512
	global_load_dword v187, v[174:175], off offset:768
	v_add_co_u32_e32 v174, vcc, 0x400, v174
	s_nop 1
	v_addc_co_u32_e32 v175, vcc, 0, v175, vcc
	global_load_dword v188, v[174:175], off
	global_load_dword v189, v[174:175], off offset:256
	global_load_dword v190, v[174:175], off offset:512
	global_load_dword v191, v[174:175], off offset:768
	v_add_co_u32_e32 v174, vcc, 0x400, v174
	s_nop 1
	v_addc_co_u32_e32 v175, vcc, 0, v175, vcc
	global_load_dword v192, v[174:175], off
	global_load_dword v193, v[174:175], off offset:256
	global_load_dword v194, v[174:175], off offset:512
	global_load_dword v195, v[174:175], off offset:768
	v_add_co_u32_e32 v174, vcc, 0x400, v174
	s_nop 1
	v_addc_co_u32_e32 v175, vcc, 0, v175, vcc
	global_load_dword v196, v[174:175], off
	global_load_dword v197, v[174:175], off offset:256
	global_load_dword v198, v[174:175], off offset:512
	global_load_dword v199, v[174:175], off offset:768
	v_add_co_u32_e32 v174, vcc, 0x400, v174
	s_nop 1
	v_addc_co_u32_e32 v175, vcc, 0, v175, vcc
	global_load_dword v200, v[174:175], off
	global_load_dword v201, v[174:175], off offset:256
	global_load_dword v234, v[174:175], off offset:512
	global_load_dword v235, v[174:175], off offset:768
	v_add_co_u32_e32 v174, vcc, 0x400, v174
	s_nop 1
	v_addc_co_u32_e32 v175, vcc, 0, v175, vcc
	global_load_dword v236, v[174:175], off
	global_load_dword v237, v[174:175], off offset:256
	global_load_dword v238, v[174:175], off offset:512
	global_load_dword v239, v[174:175], off offset:768
	v_add_co_u32_e32 v174, vcc, 0x400, v174
	s_nop 1
	v_addc_co_u32_e32 v175, vcc, 0, v175, vcc
	ds_read_b128 v[166:169], v20
	ds_read_b128 v[170:173], v20 offset:16
	s_waitcnt lgkmcnt(1)
	s_waitcnt vmcnt(31)
	v_fmac_f32_e32 v0, v166, v165
	s_waitcnt vmcnt(30)
	v_fmac_f32_e32 v0, v167, v176
	s_waitcnt vmcnt(29)
	v_fmac_f32_e32 v0, v168, v177
	s_waitcnt vmcnt(28)
	v_fmac_f32_e32 v0, v169, v178
	ds_read_b128 v[166:169], v20 offset:32
	s_waitcnt lgkmcnt(1)
	s_waitcnt vmcnt(27)
	v_fmac_f32_e32 v0, v170, v179
	s_waitcnt vmcnt(26)
	v_fmac_f32_e32 v0, v171, v180
	s_waitcnt vmcnt(25)
	v_fmac_f32_e32 v0, v172, v181
	s_waitcnt vmcnt(24)
	v_fmac_f32_e32 v0, v173, v182
	ds_read_b128 v[170:173], v20 offset:48
	s_waitcnt lgkmcnt(1)
	s_waitcnt vmcnt(23)
	v_fmac_f32_e32 v0, v166, v183
	s_waitcnt vmcnt(22)
	v_fmac_f32_e32 v0, v167, v185
	s_waitcnt vmcnt(21)
	v_fmac_f32_e32 v0, v168, v186
	s_waitcnt vmcnt(20)
	v_fmac_f32_e32 v0, v169, v187
	ds_read_b128 v[166:169], v20 offset:64
	s_waitcnt lgkmcnt(1)
	s_waitcnt vmcnt(19)
	v_fmac_f32_e32 v0, v170, v188
	s_waitcnt vmcnt(18)
	v_fmac_f32_e32 v0, v171, v189
	s_waitcnt vmcnt(17)
	v_fmac_f32_e32 v0, v172, v190
	s_waitcnt vmcnt(16)
	v_fmac_f32_e32 v0, v173, v191
	ds_read_b128 v[170:173], v20 offset:80
	s_waitcnt lgkmcnt(1)
	s_waitcnt vmcnt(15)
	v_fmac_f32_e32 v0, v166, v192
	s_waitcnt vmcnt(14)
	v_fmac_f32_e32 v0, v167, v193
	s_waitcnt vmcnt(13)
	v_fmac_f32_e32 v0, v168, v194
	s_waitcnt vmcnt(12)
	v_fmac_f32_e32 v0, v169, v195
	ds_read_b128 v[166:169], v20 offset:96
	s_waitcnt lgkmcnt(1)
	s_waitcnt vmcnt(11)
	v_fmac_f32_e32 v0, v170, v196
	s_waitcnt vmcnt(10)
	v_fmac_f32_e32 v0, v171, v197
	s_waitcnt vmcnt(9)
	v_fmac_f32_e32 v0, v172, v198
	s_waitcnt vmcnt(8)
	v_fmac_f32_e32 v0, v173, v199
	ds_read_b128 v[170:173], v20 offset:112
	s_waitcnt lgkmcnt(1)
	s_waitcnt vmcnt(7)
	v_fmac_f32_e32 v0, v166, v200
	s_waitcnt vmcnt(6)
	v_fmac_f32_e32 v0, v167, v201
	s_waitcnt vmcnt(5)
	v_fmac_f32_e32 v0, v168, v234
	s_waitcnt vmcnt(4)
	v_fmac_f32_e32 v0, v169, v235
	s_waitcnt lgkmcnt(0)
	s_waitcnt vmcnt(3)
	v_fmac_f32_e32 v0, v170, v236
	s_waitcnt vmcnt(2)
	v_fmac_f32_e32 v0, v171, v237
	s_waitcnt vmcnt(1)
	v_fmac_f32_e32 v0, v172, v238
	s_waitcnt vmcnt(0)
; __device__ NOINL void prep_filters(const LAS Params* lp, int l, bool with_ctx, LAS unsigned char* lds) {
;     ...
;         { const int pp = tid >> 6, j = tid & 63; float s = b2[j];
; #pragma unroll 4
;           for (int e = 0; e < 64; ++e) s += h1[pp * 64 + e] * w2[e * 64 + j];
;           h2[pp * 64 + j] = sinf(f2[j] * s); }
	v_fmac_f32_e32 v0, v173, v239
	global_load_dword v165, v[174:175], off
	global_load_dword v176, v[174:175], off offset:256
	global_load_dword v177, v[174:175], off offset:512
	global_load_dword v178, v[174:175], off offset:768
	v_add_co_u32_e32 v174, vcc, 0x400, v174
	s_nop 1
	v_addc_co_u32_e32 v175, vcc, 0, v175, vcc
	global_load_dword v179, v[174:175], off
	global_load_dword v180, v[174:175], off offset:256
	global_load_dword v181, v[174:175], off offset:512
	global_load_dword v182, v[174:175], off offset:768
	v_add_co_u32_e32 v174, vcc, 0x400, v174
	s_nop 1
	v_addc_co_u32_e32 v175, vcc, 0, v175, vcc
	global_load_dword v183, v[174:175], off
	global_load_dword v185, v[174:175], off offset:256
	global_load_dword v186, v[174:175], off offset:512
	global_load_dword v187, v[174:175], off offset:768
	v_add_co_u32_e32 v174, vcc, 0x400, v174
	s_nop 1
	v_addc_co_u32_e32 v175, vcc, 0, v175, vcc
	global_load_dword v188, v[174:175], off
	global_load_dword v189, v[174:175], off offset:256
	global_load_dword v190, v[174:175], off offset:512
	global_load_dword v191, v[174:175], off offset:768
	v_add_co_u32_e32 v174, vcc, 0x400, v174
	s_nop 1
	v_addc_co_u32_e32 v175, vcc, 0, v175, vcc
	global_load_dword v192, v[174:175], off
	global_load_dword v193, v[174:175], off offset:256
	global_load_dword v194, v[174:175], off offset:512
	global_load_dword v195, v[174:175], off offset:768
	v_add_co_u32_e32 v174, vcc, 0x400, v174
	s_nop 1
	v_addc_co_u32_e32 v175, vcc, 0, v175, vcc
	global_load_dword v196, v[174:175], off
	global_load_dword v197, v[174:175], off offset:256
	global_load_dword v198, v[174:175], off offset:512
	global_load_dword v199, v[174:175], off offset:768
	v_add_co_u32_e32 v174, vcc, 0x400, v174
	s_nop 1
	v_addc_co_u32_e32 v175, vcc, 0, v175, vcc
	global_load_dword v200, v[174:175], off
	global_load_dword v201, v[174:175], off offset:256
	global_load_dword v234, v[174:175], off offset:512
	global_load_dword v235, v[174:175], off offset:768
	v_add_co_u32_e32 v174, vcc, 0x400, v174
	s_nop 1
	v_addc_co_u32_e32 v175, vcc, 0, v175, vcc
	global_load_dword v236, v[174:175], off
	global_load_dword v237, v[174:175], off offset:256
	global_load_dword v238, v[174:175], off offset:512
	global_load_dword v239, v[174:175], off offset:768
	v_add_co_u32_e32 v174, vcc, 0x400, v174
	s_nop 1
	v_addc_co_u32_e32 v175, vcc, 0, v175, vcc
	ds_read_b128 v[166:169], v20 offset:128
	ds_read_b128 v[170:173], v20 offset:144
	s_waitcnt lgkmcnt(1)
	s_waitcnt vmcnt(31)
	v_fmac_f32_e32 v0, v166, v165
	s_waitcnt vmcnt(30)
	v_fmac_f32_e32 v0, v167, v176
	s_waitcnt vmcnt(29)
	v_fmac_f32_e32 v0, v168, v177
	s_waitcnt vmcnt(28)
	v_fmac_f32_e32 v0, v169, v178
	ds_read_b128 v[166:169], v20 offset:160
	s_waitcnt lgkmcnt(1)
	s_waitcnt vmcnt(27)
	v_fmac_f32_e32 v0, v170, v179
	s_waitcnt vmcnt(26)
	v_fmac_f32_e32 v0, v171, v180
	s_waitcnt vmcnt(25)
	v_fmac_f32_e32 v0, v172, v181
	s_waitcnt vmcnt(24)
	v_fmac_f32_e32 v0, v173, v182
	ds_read_b128 v[170:173], v20 offset:176
	s_waitcnt lgkmcnt(1)
	s_waitcnt vmcnt(23)
	v_fmac_f32_e32 v0, v166, v183
	s_waitcnt vmcnt(22)
	v_fmac_f32_e32 v0, v167, v185
	s_waitcnt vmcnt(21)
	v_fmac_f32_e32 v0, v168, v186
	s_waitcnt vmcnt(20)
	v_fmac_f32_e32 v0, v169, v187
	ds_read_b128 v[166:169], v20 offset:192
	s_waitcnt lgkmcnt(1)
	s_waitcnt vmcnt(19)
	v_fmac_f32_e32 v0, v170, v188
	s_waitcnt vmcnt(18)
	v_fmac_f32_e32 v0, v171, v189
	s_waitcnt vmcnt(17)
	v_fmac_f32_e32 v0, v172, v190
	s_waitcnt vmcnt(16)
	v_fmac_f32_e32 v0, v173, v191
	ds_read_b128 v[170:173], v20 offset:208
	s_waitcnt lgkmcnt(1)
	s_waitcnt vmcnt(15)
	v_fmac_f32_e32 v0, v166, v192
	s_waitcnt vmcnt(14)
	v_fmac_f32_e32 v0, v167, v193
	s_waitcnt vmcnt(13)
	v_fmac_f32_e32 v0, v168, v194
	s_waitcnt vmcnt(12)
	v_fmac_f32_e32 v0, v169, v195
	ds_read_b128 v[166:169], v20 offset:224
	s_waitcnt lgkmcnt(1)
	s_waitcnt vmcnt(11)
	v_fmac_f32_e32 v0, v170, v196
	s_waitcnt vmcnt(10)
	v_fmac_f32_e32 v0, v171, v197
	s_waitcnt vmcnt(9)
	v_fmac_f32_e32 v0, v172, v198
	s_waitcnt vmcnt(8)
	v_fmac_f32_e32 v0, v173, v199
	ds_read_b128 v[170:173], v20 offset:240
	s_waitcnt lgkmcnt(1)
	s_waitcnt vmcnt(7)
	v_fmac_f32_e32 v0, v166, v200
	s_waitcnt vmcnt(6)
	v_fmac_f32_e32 v0, v167, v201
	s_waitcnt vmcnt(5)
	v_fmac_f32_e32 v0, v168, v234
	s_waitcnt vmcnt(4)
	v_fmac_f32_e32 v0, v169, v235
	s_waitcnt lgkmcnt(0)
	s_waitcnt vmcnt(3)
	v_fmac_f32_e32 v0, v170, v236
	s_waitcnt vmcnt(2)
	v_fmac_f32_e32 v0, v171, v237
	s_waitcnt vmcnt(1)
	v_fmac_f32_e32 v0, v172, v238
	s_waitcnt vmcnt(0)
	v_fmac_f32_e32 v0, v173, v239
	v_add_u32_e32 v20, 0x100, v20
	s_movk_i32 s52, 0x4000
	s_mov_b32 s53, 0
	global_load_dword v20, v[12:13], off offset:256
	s_brev_b32 s1, 18
	s_waitcnt vmcnt(0)
	v_mul_f32_e32 v20, v0, v20
	v_and_b32_e32 v21, 0x7fffffff, v20
	v_cmp_nlt_f32_e64 s[4:5], |v20|, s1
	s_and_saveexec_b64 s[18:19], s[4:5]
	s_xor_b64 s[58:59], exec, s[18:19]
	s_cbranch_execz .LBB0_428
; __device__ NOINL void prep_filters(const LAS Params* lp, int l, bool with_ctx, LAS unsigned char* lds) {
;     ...
;           h2[pp * 64 + j] = sinf(f2[j] * s); }
	v_lshrrev_b32_e32 v0, 23, v21
	v_add_u32_e32 v0, 0xffffff88, v0
	v_cmp_lt_u32_e32 vcc, 63, v0
	s_mov_b32 s1, 0xfe5163ab
	s_nop 0
	v_cndmask_b32_e32 v22, 0, v221, vcc
	v_add_u32_e32 v0, v22, v0
	v_cmp_lt_u32_e64 s[52:53], 31, v0
	s_nop 1
	v_cndmask_b32_e64 v22, 0, v222, s[52:53]
	v_add_u32_e32 v0, v22, v0
	v_cmp_lt_u32_e64 s[54:55], 31, v0
	s_nop 1
	v_cndmask_b32_e64 v22, 0, v222, s[54:55]
	v_add_u32_e32 v37, v22, v0
	v_and_b32_e32 v0, 0x7fffff, v21
	v_or_b32_e32 v42, 0x800000, v0
	v_mad_u64_u32 v[22:23], s[4:5], v42, s1, 0
	v_mov_b32_e32 v0, v23
	s_mov_b32 s1, 0x3c439041
	v_mad_u64_u32 v[24:25], s[4:5], v42, s1, v[0:1]
	v_mov_b32_e32 v0, v25
	s_mov_b32 s1, 0xdb629599
	v_mad_u64_u32 v[26:27], s[4:5], v42, s1, v[0:1]
	v_mov_b32_e32 v0, v27
	s_mov_b32 s1, 0xf534ddc0
	v_mad_u64_u32 v[28:29], s[4:5], v42, s1, v[0:1]
	v_mov_b32_e32 v0, v29
	s_mov_b32 s1, 0xfc2757d1
	v_mad_u64_u32 v[38:39], s[4:5], v42, s1, v[0:1]
	v_mov_b32_e32 v0, v39
	s_mov_b32 s1, 0x4e441529
	v_mad_u64_u32 v[40:41], s[4:5], v42, s1, v[0:1]
	v_mov_b32_e32 v0, v41
	s_mov_b32 s1, 0xa2f9836e
	v_mad_u64_u32 v[42:43], s[4:5], v42, s1, v[0:1]
	v_cndmask_b32_e32 v23, v40, v28, vcc
	v_cndmask_b32_e32 v0, v42, v38, vcc
	v_cndmask_b32_e32 v27, v43, v40, vcc
	v_cndmask_b32_e64 v25, v0, v23, s[52:53]
	v_cndmask_b32_e64 v0, v27, v0, s[52:53]
	v_cndmask_b32_e32 v27, v38, v26, vcc
	v_cndmask_b32_e64 v23, v23, v27, s[52:53]
	v_cndmask_b32_e32 v24, v28, v24, vcc
	v_cndmask_b32_e64 v0, v0, v25, s[54:55]
	v_cndmask_b32_e64 v25, v25, v23, s[54:55]
	v_sub_u32_e32 v29, 32, v37
	v_cndmask_b32_e64 v27, v27, v24, s[52:53]
	v_alignbit_b32 v38, v0, v25, v29
	v_cmp_eq_u32_e64 s[56:57], 0, v37
	v_cndmask_b32_e64 v23, v23, v27, s[54:55]
	v_cndmask_b32_e32 v22, v26, v22, vcc
	v_cndmask_b32_e64 v0, v38, v0, s[56:57]
	v_alignbit_b32 v28, v25, v23, v29
	v_cndmask_b32_e64 v22, v24, v22, s[52:53]
	v_cndmask_b32_e64 v25, v28, v25, s[56:57]
	v_bfe_u32 v38, v0, 29, 1
	v_cndmask_b32_e64 v22, v27, v22, s[54:55]
	v_alignbit_b32 v28, v0, v25, 30
	v_sub_u32_e32 v39, 0, v38
	v_alignbit_b32 v24, v23, v22, v29
	v_xor_b32_e32 v28, v28, v39
	v_cndmask_b32_e64 v23, v24, v23, s[56:57]
	v_alignbit_b32 v24, v25, v23, 30
	v_ffbh_u32_e32 v25, v28
	v_min_u32_e32 v25, 32, v25
	v_alignbit_b32 v22, v23, v22, 30
	v_xor_b32_e32 v24, v24, v39
	v_sub_u32_e32 v26, 31, v25
	v_xor_b32_e32 v22, v22, v39
	v_alignbit_b32 v27, v28, v24, v26
	v_alignbit_b32 v22, v24, v22, v26
	v_alignbit_b32 v23, v27, v22, 9
	v_ffbh_u32_e32 v24, v23
	v_min_u32_e32 v24, 32, v24
	v_lshrrev_b32_e32 v37, 29, v0
	v_not_b32_e32 v26, v24
	v_alignbit_b32 v22, v23, v22, v26
	v_lshlrev_b32_e32 v23, 31, v37
	v_or_b32_e32 v26, 0x33000000, v23
	v_add_lshl_u32 v24, v24, v25, 23
	v_lshrrev_b32_e32 v22, 9, v22
	v_sub_u32_e32 v24, v26, v24
	v_or_b32_e32 v23, 0.5, v23
	v_lshlrev_b32_e32 v25, 23, v25
	v_or_b32_e32 v22, v24, v22
	v_lshrrev_b32_e32 v24, 9, v27
	v_sub_u32_e32 v23, v23, v25
	v_or_b32_e32 v23, v24, v23
	v_mul_f32_e32 v24, 0x3fc90fda, v23
	s_mov_b32 s1, 0x3fc90fda
	v_fma_f32 v25, v23, s1, -v24
	v_fmac_f32_e32 v25, 0x33a22168, v23
	v_fmac_f32_e32 v25, 0x3fc90fda, v22
	v_lshrrev_b32_e32 v0, 30, v0
	v_add_f32_e32 v22, v24, v25
	v_add_u32_e32 v0, v38, v0
